# G2 Z stores use the default cache policy instead of nt so the LayerNorm phase re-reads them from cache
# speedup vs baseline: 1.0378x; 1.0119x over previous
.LBB0_1373:
	s_mov_b64 s[14:15], 0x9080000
	s_lshl_b32 s16, s51, 8
	v_readlane_b32 s18, v252, 0
	v_readlane_b32 s19, v252, 1
	s_add_u32 s14, s18, s14
	s_addc_u32 s15, s19, s15
	s_ashr_i32 s17, s16, 31
	s_lshl_b64 s[18:19], s[16:17], 1
	s_add_u32 s7, s14, s18
	s_addc_u32 s9, s15, s19
	s_add_u32 s18, s7, s47
	s_addc_u32 s19, s9, 0
	v_lshl_add_u32 v130, s50, 8, v234
	v_lshl_add_u64 v[132:133], s[18:19], 0, v[0:1]
	s_mov_b32 s18, 0xf7f80000
	s_mov_b32 s19, -1
	v_ashrrev_i32_e32 v131, 31, v130
	v_lshl_add_u64 v[132:133], v[132:133], 0, s[18:19]
	v_lshlrev_b64 v[242:243], 11, v[130:131]
	v_lshl_add_u64 v[134:135], v[132:133], 0, v[242:243]
	global_load_dwordx4 v[238:241], v[134:135], off
	global_load_dwordx4 v[186:189], v[134:135], off offset:256
	v_or_b32_e32 v134, 16, v130
	v_ashrrev_i32_e32 v135, 31, v134
	v_lshlrev_b64 v[222:223], 11, v[134:135]
	v_lshl_add_u64 v[134:135], v[132:133], 0, v[222:223]
	global_load_dwordx4 v[182:185], v[134:135], off
	global_load_dwordx4 v[178:181], v[134:135], off offset:256
	v_or_b32_e32 v134, 32, v130
	v_ashrrev_i32_e32 v135, 31, v134
	v_lshlrev_b64 v[220:221], 11, v[134:135]
	v_lshl_add_u64 v[134:135], v[132:133], 0, v[220:221]
	global_load_dwordx4 v[174:177], v[134:135], off
	global_load_dwordx4 v[170:173], v[134:135], off offset:256
	v_or_b32_e32 v134, 48, v130
	v_ashrrev_i32_e32 v135, 31, v134
	v_lshlrev_b64 v[218:219], 11, v[134:135]
	v_lshl_add_u64 v[134:135], v[132:133], 0, v[218:219]
	global_load_dwordx4 v[166:169], v[134:135], off
	global_load_dwordx4 v[162:165], v[134:135], off offset:256
	v_add_u32_e32 v134, 0x80, v130
	v_ashrrev_i32_e32 v135, 31, v134
	v_lshlrev_b64 v[216:217], 11, v[134:135]
	v_lshl_add_u64 v[134:135], v[132:133], 0, v[216:217]
	global_load_dwordx4 v[158:161], v[134:135], off
	global_load_dwordx4 v[154:157], v[134:135], off offset:256
	v_add_u32_e32 v134, 0x90, v130
	v_ashrrev_i32_e32 v135, 31, v134
	v_lshlrev_b64 v[214:215], 11, v[134:135]
	v_lshl_add_u64 v[134:135], v[132:133], 0, v[214:215]
	global_load_dwordx4 v[150:153], v[134:135], off
	global_load_dwordx4 v[146:149], v[134:135], off offset:256
	v_add_u32_e32 v134, 0xa0, v130
	v_add_u32_e32 v130, 0xb0, v130
	v_ashrrev_i32_e32 v135, 31, v134
	v_ashrrev_i32_e32 v131, 31, v130
	v_lshlrev_b64 v[212:213], 11, v[134:135]
	v_lshlrev_b64 v[210:211], 11, v[130:131]
	v_or_b32_e32 v244, s16, v236
	v_lshl_add_u64 v[134:135], v[132:133], 0, v[212:213]
	v_lshl_add_u64 v[130:131], v[132:133], 0, v[210:211]
	v_ashrrev_i32_e32 v245, 31, v244
	global_load_dwordx4 v[142:145], v[134:135], off
	global_load_dwordx4 v[138:141], v[134:135], off offset:256
	s_nop 0
	global_load_dwordx4 v[134:137], v[130:131], off
	s_nop 0
	global_load_dwordx4 v[130:133], v[130:131], off offset:256
	v_lshl_add_u64 v[242:243], s[14:15], 0, v[242:243]
	s_andn2_b64 vcc, exec, s[38:39]
	s_mov_b64 s[76:77], 0x21200200
	s_waitcnt vmcnt(15)
	v_lshlrev_b32_e32 v225, 16, v238
	v_fmamk_f32 v126, v225, 0x3fb504f3, v126
	v_and_b32_e32 v225, 0xffff0000, v238
	v_fmamk_f32 v127, v225, 0x3fb504f3, v127
	v_lshlrev_b32_e32 v225, 16, v239
	v_fmamk_f32 v128, v225, 0x3fb504f3, v128
	v_and_b32_e32 v225, 0xffff0000, v239
	v_fmac_f32_e32 v129, 0x3fb504f3, v225
	v_lshlrev_b32_e32 v225, 16, v240
	v_fmamk_f32 v122, v225, 0x3fb504f3, v122
	v_and_b32_e32 v225, 0xffff0000, v240
	v_fmamk_f32 v123, v225, 0x3fb504f3, v123
	v_lshlrev_b32_e32 v225, 16, v241
	v_fmamk_f32 v124, v225, 0x3fb504f3, v124
	v_and_b32_e32 v225, 0xffff0000, v241
	v_fmac_f32_e32 v125, 0x3fb504f3, v225
	v_cvt_pk_bf16_f32 v126, v126, v127
	v_cvt_pk_bf16_f32 v127, v128, v129
	v_cvt_pk_bf16_f32 v128, v122, v123
	v_lshlrev_b64 v[122:123], 1, v[244:245]
	v_cvt_pk_bf16_f32 v129, v124, v125
	v_lshl_add_u64 v[124:125], v[242:243], 0, v[122:123]
	global_store_dwordx4 v[124:125], v[126:129], off
	s_waitcnt vmcnt(15)
	s_nop 1
	v_lshlrev_b32_e32 v126, 16, v186
	v_fmamk_f32 v118, v126, 0x3fb504f3, v118
	v_and_b32_e32 v126, 0xffff0000, v186
	v_fmamk_f32 v119, v126, 0x3fb504f3, v119
	v_lshlrev_b32_e32 v126, 16, v187
	v_fmamk_f32 v120, v126, 0x3fb504f3, v120
	v_and_b32_e32 v126, 0xffff0000, v187
	v_fmac_f32_e32 v121, 0x3fb504f3, v126
	v_lshlrev_b32_e32 v126, 16, v188
	v_fmamk_f32 v126, v126, 0x3fb504f3, v110
	v_and_b32_e32 v110, 0xffff0000, v188
	v_fmamk_f32 v127, v110, 0x3fb504f3, v111
	v_lshlrev_b32_e32 v110, 16, v189
	v_fmamk_f32 v128, v110, 0x3fb504f3, v112
	v_and_b32_e32 v110, 0xffff0000, v189
	v_fmac_f32_e32 v113, 0x3fb504f3, v110
	v_cvt_pk_bf16_f32 v110, v118, v119
	v_cvt_pk_bf16_f32 v111, v120, v121
	v_cvt_pk_bf16_f32 v112, v126, v127
	v_cvt_pk_bf16_f32 v113, v128, v113
	global_store_dwordx4 v[124:125], v[110:113], off offset:256
	s_waitcnt vmcnt(15)
	s_nop 1
	v_and_b32_e32 v113, 0xffff0000, v182
	v_fmamk_f32 v113, v113, 0x3fb504f3, v115
	v_and_b32_e32 v115, 0xffff0000, v183
	v_lshlrev_b32_e32 v112, 16, v182
	v_fmac_f32_e32 v117, 0x3fb504f3, v115
	v_lshlrev_b32_e32 v115, 16, v184
	v_fmamk_f32 v112, v112, 0x3fb504f3, v114
	v_lshlrev_b32_e32 v114, 16, v183
	v_fmamk_f32 v115, v115, 0x3fb504f3, v106
	v_and_b32_e32 v106, 0xffff0000, v184
	v_fmamk_f32 v114, v114, 0x3fb504f3, v116
	v_fmamk_f32 v116, v106, 0x3fb504f3, v107
	v_lshlrev_b32_e32 v106, 16, v185
	v_lshl_add_u64 v[110:111], s[14:15], 0, v[222:223]
	v_fmamk_f32 v118, v106, 0x3fb504f3, v108
	v_and_b32_e32 v106, 0xffff0000, v185
	v_fmac_f32_e32 v109, 0x3fb504f3, v106
	v_cvt_pk_bf16_f32 v106, v112, v113
	v_lshl_add_u64 v[110:111], v[110:111], 0, v[122:123]
	v_cvt_pk_bf16_f32 v107, v114, v117
	v_cvt_pk_bf16_f32 v108, v115, v116
	v_cvt_pk_bf16_f32 v109, v118, v109
	global_store_dwordx4 v[110:111], v[106:109], off
	s_waitcnt vmcnt(15)
	s_nop 1
	v_lshlrev_b32_e32 v106, 16, v178
	v_fmamk_f32 v102, v106, 0x3fb504f3, v102
	v_and_b32_e32 v106, 0xffff0000, v178
	v_fmamk_f32 v103, v106, 0x3fb504f3, v103
	v_lshlrev_b32_e32 v106, 16, v179
	v_fmamk_f32 v104, v106, 0x3fb504f3, v104
	v_and_b32_e32 v106, 0xffff0000, v179
	v_fmac_f32_e32 v105, 0x3fb504f3, v106
	v_lshlrev_b32_e32 v106, 16, v180
	v_fmamk_f32 v106, v106, 0x3fb504f3, v94
	v_and_b32_e32 v94, 0xffff0000, v180
	v_fmamk_f32 v107, v94, 0x3fb504f3, v95
	v_lshlrev_b32_e32 v94, 16, v181
	v_fmamk_f32 v108, v94, 0x3fb504f3, v96
	v_and_b32_e32 v94, 0xffff0000, v181
	v_fmac_f32_e32 v97, 0x3fb504f3, v94
	v_cvt_pk_bf16_f32 v94, v102, v103
	v_cvt_pk_bf16_f32 v95, v104, v105
	v_cvt_pk_bf16_f32 v96, v106, v107
	v_cvt_pk_bf16_f32 v97, v108, v97
	global_store_dwordx4 v[110:111], v[94:97], off offset:256
	s_waitcnt vmcnt(15)
	s_nop 1
	v_and_b32_e32 v97, 0xffff0000, v174
	v_fmamk_f32 v97, v97, 0x3fb504f3, v99
	v_and_b32_e32 v99, 0xffff0000, v175
	v_lshlrev_b32_e32 v96, 16, v174
	v_fmac_f32_e32 v101, 0x3fb504f3, v99
	v_lshlrev_b32_e32 v99, 16, v176
	v_fmamk_f32 v96, v96, 0x3fb504f3, v98
	v_lshlrev_b32_e32 v98, 16, v175
	v_fmamk_f32 v99, v99, 0x3fb504f3, v90
	v_and_b32_e32 v90, 0xffff0000, v176
	v_fmamk_f32 v98, v98, 0x3fb504f3, v100
	v_fmamk_f32 v100, v90, 0x3fb504f3, v91
	v_lshlrev_b32_e32 v90, 16, v177
	v_lshl_add_u64 v[94:95], s[14:15], 0, v[220:221]
	v_fmamk_f32 v102, v90, 0x3fb504f3, v92
	v_and_b32_e32 v90, 0xffff0000, v177
	v_fmac_f32_e32 v93, 0x3fb504f3, v90
	v_cvt_pk_bf16_f32 v90, v96, v97
	v_lshl_add_u64 v[94:95], v[94:95], 0, v[122:123]
	v_cvt_pk_bf16_f32 v91, v98, v101
	v_cvt_pk_bf16_f32 v92, v99, v100
	v_cvt_pk_bf16_f32 v93, v102, v93
	global_store_dwordx4 v[94:95], v[90:93], off
	s_waitcnt vmcnt(15)
	s_nop 1
	v_lshlrev_b32_e32 v90, 16, v170
	v_fmamk_f32 v86, v90, 0x3fb504f3, v86
	v_and_b32_e32 v90, 0xffff0000, v170
	v_fmamk_f32 v87, v90, 0x3fb504f3, v87
	v_lshlrev_b32_e32 v90, 16, v171
	v_fmamk_f32 v88, v90, 0x3fb504f3, v88
	v_and_b32_e32 v90, 0xffff0000, v171
	v_fmac_f32_e32 v89, 0x3fb504f3, v90
	v_lshlrev_b32_e32 v90, 16, v172
	v_fmamk_f32 v90, v90, 0x3fb504f3, v78
	v_and_b32_e32 v78, 0xffff0000, v172
	v_fmamk_f32 v91, v78, 0x3fb504f3, v79
	v_lshlrev_b32_e32 v78, 16, v173
	v_fmamk_f32 v92, v78, 0x3fb504f3, v80
	v_and_b32_e32 v78, 0xffff0000, v173
	v_fmac_f32_e32 v81, 0x3fb504f3, v78
	v_cvt_pk_bf16_f32 v78, v86, v87
	v_cvt_pk_bf16_f32 v79, v88, v89
	v_cvt_pk_bf16_f32 v80, v90, v91
	v_cvt_pk_bf16_f32 v81, v92, v81
	global_store_dwordx4 v[94:95], v[78:81], off offset:256
	s_waitcnt vmcnt(15)
	s_nop 1
	v_and_b32_e32 v81, 0xffff0000, v166
	v_fmamk_f32 v81, v81, 0x3fb504f3, v83
	v_and_b32_e32 v83, 0xffff0000, v167
	v_lshlrev_b32_e32 v80, 16, v166
	v_fmac_f32_e32 v85, 0x3fb504f3, v83
	v_lshlrev_b32_e32 v83, 16, v168
	v_fmamk_f32 v80, v80, 0x3fb504f3, v82
	v_lshlrev_b32_e32 v82, 16, v167
	v_fmamk_f32 v83, v83, 0x3fb504f3, v74
	v_and_b32_e32 v74, 0xffff0000, v168
	v_fmamk_f32 v82, v82, 0x3fb504f3, v84
	v_fmamk_f32 v84, v74, 0x3fb504f3, v75
	v_lshlrev_b32_e32 v74, 16, v169
	v_lshl_add_u64 v[78:79], s[14:15], 0, v[218:219]
	v_fmamk_f32 v86, v74, 0x3fb504f3, v76
	v_and_b32_e32 v74, 0xffff0000, v169
	v_fmac_f32_e32 v77, 0x3fb504f3, v74
	v_cvt_pk_bf16_f32 v74, v80, v81
	v_lshl_add_u64 v[78:79], v[78:79], 0, v[122:123]
	v_cvt_pk_bf16_f32 v75, v82, v85
	v_cvt_pk_bf16_f32 v76, v83, v84
	v_cvt_pk_bf16_f32 v77, v86, v77
	global_store_dwordx4 v[78:79], v[74:77], off
	s_waitcnt vmcnt(15)
	s_nop 1
	v_lshlrev_b32_e32 v74, 16, v162
	v_fmamk_f32 v70, v74, 0x3fb504f3, v70
	v_and_b32_e32 v74, 0xffff0000, v162
	v_fmamk_f32 v71, v74, 0x3fb504f3, v71
	v_lshlrev_b32_e32 v74, 16, v163
	v_fmamk_f32 v72, v74, 0x3fb504f3, v72
	v_and_b32_e32 v74, 0xffff0000, v163
	v_fmac_f32_e32 v73, 0x3fb504f3, v74
	v_lshlrev_b32_e32 v74, 16, v164
	v_fmamk_f32 v74, v74, 0x3fb504f3, v66
	v_and_b32_e32 v66, 0xffff0000, v164
	v_fmamk_f32 v75, v66, 0x3fb504f3, v67
	v_lshlrev_b32_e32 v66, 16, v165
	v_fmamk_f32 v76, v66, 0x3fb504f3, v68
	v_and_b32_e32 v66, 0xffff0000, v165
	v_fmac_f32_e32 v69, 0x3fb504f3, v66
	v_cvt_pk_bf16_f32 v66, v70, v71
	v_cvt_pk_bf16_f32 v67, v72, v73
	v_cvt_pk_bf16_f32 v68, v74, v75
	v_cvt_pk_bf16_f32 v69, v76, v69
	global_store_dwordx4 v[78:79], v[66:69], off offset:256
	s_waitcnt vmcnt(15)
	s_nop 1
	v_lshlrev_b32_e32 v68, 16, v158
	v_fmamk_f32 v62, v68, 0x3fb504f3, v62
	v_and_b32_e32 v68, 0xffff0000, v158
	v_fmamk_f32 v63, v68, 0x3fb504f3, v63
	v_lshlrev_b32_e32 v68, 16, v159
	v_fmamk_f32 v64, v68, 0x3fb504f3, v64
	v_and_b32_e32 v68, 0xffff0000, v159
	v_fmac_f32_e32 v65, 0x3fb504f3, v68
	v_lshlrev_b32_e32 v68, 16, v160
	v_fmamk_f32 v68, v68, 0x3fb504f3, v58
	v_and_b32_e32 v58, 0xffff0000, v160
	v_fmamk_f32 v69, v58, 0x3fb504f3, v59
	v_lshlrev_b32_e32 v58, 16, v161
	v_lshl_add_u64 v[66:67], s[14:15], 0, v[216:217]
	v_fmamk_f32 v70, v58, 0x3fb504f3, v60
	v_and_b32_e32 v58, 0xffff0000, v161
	v_fmac_f32_e32 v61, 0x3fb504f3, v58
	v_cvt_pk_bf16_f32 v58, v62, v63
	v_lshl_add_u64 v[62:63], v[66:67], 0, v[122:123]
	v_cvt_pk_bf16_f32 v59, v64, v65
	v_cvt_pk_bf16_f32 v60, v68, v69
	v_cvt_pk_bf16_f32 v61, v70, v61
	global_store_dwordx4 v[62:63], v[58:61], off
	s_waitcnt vmcnt(15)
	s_nop 1
	v_lshlrev_b32_e32 v58, 16, v154
	v_fmamk_f32 v54, v58, 0x3fb504f3, v54
	v_and_b32_e32 v58, 0xffff0000, v154
	v_fmamk_f32 v55, v58, 0x3fb504f3, v55
	v_lshlrev_b32_e32 v58, 16, v155
	v_fmamk_f32 v56, v58, 0x3fb504f3, v56
	v_and_b32_e32 v58, 0xffff0000, v155
	v_fmac_f32_e32 v57, 0x3fb504f3, v58
	v_lshlrev_b32_e32 v58, 16, v156
	v_fmamk_f32 v58, v58, 0x3fb504f3, v46
	v_and_b32_e32 v46, 0xffff0000, v156
	v_fmamk_f32 v59, v46, 0x3fb504f3, v47
	v_lshlrev_b32_e32 v46, 16, v157
	v_fmamk_f32 v60, v46, 0x3fb504f3, v48
	v_and_b32_e32 v46, 0xffff0000, v157
	v_fmac_f32_e32 v49, 0x3fb504f3, v46
	v_cvt_pk_bf16_f32 v46, v54, v55
	v_cvt_pk_bf16_f32 v47, v56, v57
	v_cvt_pk_bf16_f32 v48, v58, v59
	v_cvt_pk_bf16_f32 v49, v60, v49
	global_store_dwordx4 v[62:63], v[46:49], off offset:256
	s_waitcnt vmcnt(15)
	s_nop 1
	v_and_b32_e32 v49, 0xffff0000, v150
	v_fmamk_f32 v49, v49, 0x3fb504f3, v51
	v_and_b32_e32 v51, 0xffff0000, v151
	v_lshlrev_b32_e32 v48, 16, v150
	v_fmac_f32_e32 v53, 0x3fb504f3, v51
	v_lshlrev_b32_e32 v51, 16, v152
	v_fmamk_f32 v48, v48, 0x3fb504f3, v50
	v_lshlrev_b32_e32 v50, 16, v151
	v_fmamk_f32 v51, v51, 0x3fb504f3, v42
	v_and_b32_e32 v42, 0xffff0000, v152
	v_fmamk_f32 v50, v50, 0x3fb504f3, v52
	v_fmamk_f32 v52, v42, 0x3fb504f3, v43
	v_lshlrev_b32_e32 v42, 16, v153
	v_lshl_add_u64 v[46:47], s[14:15], 0, v[214:215]
	v_fmamk_f32 v54, v42, 0x3fb504f3, v44
	v_and_b32_e32 v42, 0xffff0000, v153
	v_fmac_f32_e32 v45, 0x3fb504f3, v42
	v_cvt_pk_bf16_f32 v42, v48, v49
	v_lshl_add_u64 v[46:47], v[46:47], 0, v[122:123]
	v_cvt_pk_bf16_f32 v43, v50, v53
	v_cvt_pk_bf16_f32 v44, v51, v52
	v_cvt_pk_bf16_f32 v45, v54, v45
	global_store_dwordx4 v[46:47], v[42:45], off
	s_waitcnt vmcnt(15)
	s_nop 1
	v_lshlrev_b32_e32 v42, 16, v146
	v_fmamk_f32 v38, v42, 0x3fb504f3, v38
	v_and_b32_e32 v42, 0xffff0000, v146
	v_fmamk_f32 v39, v42, 0x3fb504f3, v39
	v_lshlrev_b32_e32 v42, 16, v147
	v_fmamk_f32 v40, v42, 0x3fb504f3, v40
	v_and_b32_e32 v42, 0xffff0000, v147
	v_fmac_f32_e32 v41, 0x3fb504f3, v42
	v_lshlrev_b32_e32 v42, 16, v148
	v_fmamk_f32 v42, v42, 0x3fb504f3, v30
	v_and_b32_e32 v30, 0xffff0000, v148
	v_fmamk_f32 v43, v30, 0x3fb504f3, v31
	v_lshlrev_b32_e32 v30, 16, v149
	v_fmamk_f32 v44, v30, 0x3fb504f3, v32
	v_and_b32_e32 v30, 0xffff0000, v149
	v_fmac_f32_e32 v33, 0x3fb504f3, v30
	v_cvt_pk_bf16_f32 v30, v38, v39
	v_cvt_pk_bf16_f32 v31, v40, v41
	v_cvt_pk_bf16_f32 v32, v42, v43
	v_cvt_pk_bf16_f32 v33, v44, v33
	global_store_dwordx4 v[46:47], v[30:33], off offset:256
	s_waitcnt vmcnt(15)
	s_nop 1
	v_and_b32_e32 v33, 0xffff0000, v142
	v_fmamk_f32 v33, v33, 0x3fb504f3, v35
	v_and_b32_e32 v35, 0xffff0000, v143
	v_lshlrev_b32_e32 v32, 16, v142
	v_fmac_f32_e32 v37, 0x3fb504f3, v35
	v_lshlrev_b32_e32 v35, 16, v144
	v_fmamk_f32 v32, v32, 0x3fb504f3, v34
	v_lshlrev_b32_e32 v34, 16, v143
	v_fmamk_f32 v35, v35, 0x3fb504f3, v26
	v_and_b32_e32 v26, 0xffff0000, v144
	v_fmamk_f32 v34, v34, 0x3fb504f3, v36
	v_fmamk_f32 v36, v26, 0x3fb504f3, v27
	v_lshlrev_b32_e32 v26, 16, v145
	v_lshl_add_u64 v[30:31], s[14:15], 0, v[212:213]
	v_fmamk_f32 v38, v26, 0x3fb504f3, v28
	v_and_b32_e32 v26, 0xffff0000, v145
	v_fmac_f32_e32 v29, 0x3fb504f3, v26
	v_cvt_pk_bf16_f32 v26, v32, v33
	v_lshl_add_u64 v[30:31], v[30:31], 0, v[122:123]
	v_cvt_pk_bf16_f32 v27, v34, v37
	v_cvt_pk_bf16_f32 v28, v35, v36
	v_cvt_pk_bf16_f32 v29, v38, v29
	global_store_dwordx4 v[30:31], v[26:29], off
	s_waitcnt vmcnt(15)
	s_nop 1
	v_lshlrev_b32_e32 v26, 16, v138
	v_fmamk_f32 v22, v26, 0x3fb504f3, v22
	v_and_b32_e32 v26, 0xffff0000, v138
	v_fmamk_f32 v23, v26, 0x3fb504f3, v23
	v_lshlrev_b32_e32 v26, 16, v139
	v_fmamk_f32 v24, v26, 0x3fb504f3, v24
	v_and_b32_e32 v26, 0xffff0000, v139
	v_fmac_f32_e32 v25, 0x3fb504f3, v26
	v_lshlrev_b32_e32 v26, 16, v140
	v_fmamk_f32 v26, v26, 0x3fb504f3, v14
	v_and_b32_e32 v14, 0xffff0000, v140
	v_fmamk_f32 v27, v14, 0x3fb504f3, v15
	v_lshlrev_b32_e32 v14, 16, v141
	v_fmamk_f32 v28, v14, 0x3fb504f3, v16
	v_and_b32_e32 v14, 0xffff0000, v141
	v_fmac_f32_e32 v17, 0x3fb504f3, v14
	v_cvt_pk_bf16_f32 v14, v22, v23
	v_cvt_pk_bf16_f32 v15, v24, v25
	v_cvt_pk_bf16_f32 v16, v26, v27
	v_cvt_pk_bf16_f32 v17, v28, v17
	global_store_dwordx4 v[30:31], v[14:17], off offset:256
	s_waitcnt vmcnt(15)
	s_nop 1
	v_and_b32_e32 v17, 0xffff0000, v134
	v_fmamk_f32 v17, v17, 0x3fb504f3, v19
	v_and_b32_e32 v19, 0xffff0000, v135
	v_lshlrev_b32_e32 v16, 16, v134
	v_fmac_f32_e32 v21, 0x3fb504f3, v19
	v_lshlrev_b32_e32 v19, 16, v136
	v_fmamk_f32 v16, v16, 0x3fb504f3, v18
	v_lshlrev_b32_e32 v18, 16, v135
	v_fmamk_f32 v19, v19, 0x3fb504f3, v10
	v_and_b32_e32 v10, 0xffff0000, v136
	v_fmamk_f32 v18, v18, 0x3fb504f3, v20
	v_fmamk_f32 v20, v10, 0x3fb504f3, v11
	v_lshlrev_b32_e32 v10, 16, v137
	v_lshl_add_u64 v[14:15], s[14:15], 0, v[210:211]
	v_fmamk_f32 v22, v10, 0x3fb504f3, v12
	v_and_b32_e32 v10, 0xffff0000, v137
	v_fmac_f32_e32 v13, 0x3fb504f3, v10
	v_cvt_pk_bf16_f32 v10, v16, v17
	v_lshl_add_u64 v[14:15], v[14:15], 0, v[122:123]
	v_cvt_pk_bf16_f32 v11, v18, v21
	v_cvt_pk_bf16_f32 v12, v19, v20
	v_cvt_pk_bf16_f32 v13, v22, v13
	global_store_dwordx4 v[14:15], v[10:13], off
	s_waitcnt vmcnt(15)
	s_mov_b64 s[14:15], -1
	s_nop 0
	v_lshlrev_b32_e32 v10, 16, v130
	v_fmamk_f32 v6, v10, 0x3fb504f3, v6
	v_and_b32_e32 v10, 0xffff0000, v130
	v_fmamk_f32 v7, v10, 0x3fb504f3, v7
	v_lshlrev_b32_e32 v10, 16, v131
	v_fmamk_f32 v8, v10, 0x3fb504f3, v8
	v_and_b32_e32 v10, 0xffff0000, v131
	v_fmac_f32_e32 v9, 0x3fb504f3, v10
	v_lshlrev_b32_e32 v10, 16, v132
	v_fmamk_f32 v10, v10, 0x3fb504f3, v2
	v_and_b32_e32 v2, 0xffff0000, v132
	v_fmamk_f32 v11, v2, 0x3fb504f3, v3
	v_lshlrev_b32_e32 v2, 16, v133
	v_fmamk_f32 v12, v2, 0x3fb504f3, v4
	v_and_b32_e32 v2, 0xffff0000, v133
	v_fmac_f32_e32 v5, 0x3fb504f3, v2
	v_cvt_pk_bf16_f32 v2, v6, v7
	v_cvt_pk_bf16_f32 v3, v8, v9
	v_cvt_pk_bf16_f32 v4, v10, v11
	v_cvt_pk_bf16_f32 v5, v12, v5
	global_store_dwordx4 v[14:15], v[2:5], off offset:256
	s_cbranch_vccnz .LBB0_1362
	s_andn2_b64 vcc, exec, s[0:1]
	s_cbranch_vccnz .LBB0_1361
	s_barrier
	s_branch .LBB0_1361
